# selection ranking region fully by hand: importance sums read in one LDS batch, no spill/reload traffic
# speedup vs baseline: 1.0015x; 1.0015x over previous
; DI void attn_phase(const Params& p, const int layer, const int wid_s) {
;     ...
;           for (int j = 0; j < 4; ++j) fin[(hp * 16 + dt * 4 + j) * 64] = o[dt][j] * gate_c;
;       }
;       unsigned mk = (2u << cur) - 1u;
;       if (cur >= 8) {
;       float impv[8];
;       __syncthreads();
; #pragma unroll
;       for (int nt = 0; nt < 8; ++nt) {
;         const float mine = impx[(wave * 8 + nt) * 64], other = impx[((wave ^ 4) * 8 + nt) * 64];
;         const float im = hpair == 0 ? mine + other : other + mine;
;         const int jb = nt * 4 + fql;
;         const bool forced = (jb == 0) || (jb == cur) || (jb == cur - 1);
;         impv[nt] = jb <= cur ? im + (forced ? 1e6f : 0.f) : NEGF;
;         impb[jb] = impv[nt];
;       }
;       __syncthreads();
.LBB0_332:
	v_cvt_f32_f16_sdwa v0, v121 dst_sel:DWORD dst_unused:UNUSED_PAD src0_sel:WORD_1
	v_mul_f32_e32 v0, 0xbfb8aa3b, v0
	v_exp_f32_e32 v0, v0
	s_nop 0
	v_add_f32_e32 v0, 1.0, v0
	v_div_scale_f32 v2, s[4:5], v0, v0, 1.0
	v_rcp_f32_e32 v3, v2
	v_div_scale_f32 v5, vcc, 1.0, v0, 1.0
	s_lshl_b32 s4, 2, s54
	v_fma_f32 v6, -v2, v3, 1.0
	v_fmac_f32_e32 v3, v6, v3
	v_mul_f32_e32 v6, v5, v3
	v_fma_f32 v7, -v2, v6, v5
	v_fmac_f32_e32 v6, v7, v3
	v_fma_f32 v2, -v2, v6, v5
	v_div_fmas_f32 v2, v2, v3, v6
	v_div_fixup_f32 v0, v2, v0, 1.0
	v_mul_f32_e32 v2, v0, v36
	v_mul_f32_e32 v3, v0, v37
	v_mul_f32_e32 v5, v0, v38
	v_mul_f32_e32 v6, v0, v39
	v_mul_f32_e32 v7, v0, v28
	ds_write2st64_b32 v188, v2, v3 offset0:168 offset1:169
	ds_write2st64_b32 v188, v5, v6 offset0:170 offset1:171
	v_mul_f32_e32 v2, v0, v29
	ds_write2st64_b32 v188, v7, v2 offset0:172 offset1:173
	v_mul_f32_e32 v2, v0, v30
	v_mul_f32_e32 v3, v0, v31
	ds_write2st64_b32 v188, v2, v3 offset0:174 offset1:175
	v_mul_f32_e32 v2, v0, v32
	v_mul_f32_e32 v3, v0, v33
	ds_write2st64_b32 v188, v2, v3 offset0:176 offset1:177
	v_mul_f32_e32 v2, v0, v34
	v_mul_f32_e32 v3, v0, v35
	ds_write2st64_b32 v188, v2, v3 offset0:178 offset1:179
	v_mul_f32_e32 v2, v0, v24
	v_mul_f32_e32 v3, v0, v25
	s_add_i32 s4, s4, -1
	ds_write2st64_b32 v188, v2, v3 offset0:180 offset1:181
	v_mul_f32_e32 v2, v0, v26
	v_mul_f32_e32 v0, v0, v27
	s_and_b64 vcc, exec, s[0:1]
	v_mov_b32_e32 v5, s4
	ds_write2st64_b32 v188, v2, v0 offset0:182 offset1:183
	s_cbranch_vccnz .LBB0_334
	s_waitcnt lgkmcnt(0)
	s_barrier
	ds_read_b32 v198, v151 offset:22656
	ds_read_b32 v199, v151 offset:22912
	ds_read_b32 v200, v151 offset:23168
	ds_read_b32 v201, v151 offset:23424
	ds_read_b32 v202, v151 offset:23680
	ds_read_b32 v203, v151 offset:23936
	ds_read_b32 v204, v151 offset:24192
	ds_read_b32 v205, v151 offset:24448
	ds_read_b32 v206, v182 offset:22656
	ds_read_b32 v207, v182 offset:22912
	ds_read_b32 v208, v182 offset:23168
	ds_read_b32 v209, v182 offset:23424
	ds_read_b32 v210, v182 offset:23680
	ds_read_b32 v211, v182 offset:23936
	ds_read_b32 v212, v182 offset:24192
	ds_read_b32 v213, v182 offset:24448
	s_add_i32 s6, s54, -1
	v_lshl_add_u32 v24, v123, 2, v147
	v_add_u32_e32 v238, 0, v123
	v_add_u32_e32 v239, 4, v123
	v_add_u32_e32 v240, 8, v123
	v_add_u32_e32 v241, 12, v123
	v_add_u32_e32 v242, 16, v123
	v_add_u32_e32 v243, 20, v123
	v_add_u32_e32 v244, 24, v123
	v_add_u32_e32 v245, 28, v123
	s_waitcnt lgkmcnt(0)
	v_cmp_eq_u32_e64 s[8:9], 0, v238
	v_cmp_eq_u32_e64 s[10:11], s54, v238
	v_cmp_eq_u32_e64 s[12:13], s6, v238
	v_add_f32_e32 v198, v198, v206
	s_or_b64 s[8:9], s[8:9], s[10:11]
	s_or_b64 s[8:9], s[8:9], s[12:13]
	v_cmp_lt_i32_e64 s[14:15], s54, v238
	s_nop 0
	v_cndmask_b32_e64 v0, 0, v159, s[8:9]
	s_nop 0
	v_add_f32_e32 v198, v0, v198
	v_cndmask_b32_e64 v39, v198, v4, s[14:15]
	ds_write_b32 v24, v39 offset:4224
	v_cmp_eq_u32_e64 s[8:9], 0, v239
	v_cmp_eq_u32_e64 s[10:11], s54, v239
	v_cmp_eq_u32_e64 s[12:13], s6, v239
	v_add_f32_e32 v199, v199, v207
	s_or_b64 s[8:9], s[8:9], s[10:11]
	s_or_b64 s[8:9], s[8:9], s[12:13]
	v_cmp_lt_i32_e64 s[14:15], s54, v239
	s_nop 0
	v_cndmask_b32_e64 v0, 0, v159, s[8:9]
	s_nop 0
	v_add_f32_e32 v199, v0, v199
	v_cndmask_b32_e64 v40, v199, v4, s[14:15]
	ds_write_b32 v24, v40 offset:4240
	v_cmp_eq_u32_e64 s[8:9], 0, v240
	v_cmp_eq_u32_e64 s[10:11], s54, v240
	v_cmp_eq_u32_e64 s[12:13], s6, v240
	v_add_f32_e32 v200, v200, v208
	s_or_b64 s[8:9], s[8:9], s[10:11]
	s_or_b64 s[8:9], s[8:9], s[12:13]
	v_cmp_lt_i32_e64 s[14:15], s54, v240
	s_nop 0
	v_cndmask_b32_e64 v0, 0, v159, s[8:9]
	s_nop 0
	v_add_f32_e32 v200, v0, v200
	v_cndmask_b32_e64 v38, v200, v4, s[14:15]
	ds_write_b32 v24, v38 offset:4256
	v_cmp_eq_u32_e64 s[8:9], 0, v241
	v_cmp_eq_u32_e64 s[10:11], s54, v241
	v_cmp_eq_u32_e64 s[12:13], s6, v241
	v_add_f32_e32 v201, v201, v209
	s_or_b64 s[8:9], s[8:9], s[10:11]
	s_or_b64 s[8:9], s[8:9], s[12:13]
	v_cmp_lt_i32_e64 s[14:15], s54, v241
	s_nop 0
	v_cndmask_b32_e64 v0, 0, v159, s[8:9]
	s_nop 0
	v_add_f32_e32 v201, v0, v201
	v_cndmask_b32_e64 v37, v201, v4, s[14:15]
	ds_write_b32 v24, v37 offset:4272
	v_cmp_eq_u32_e64 s[8:9], 0, v242
	v_cmp_eq_u32_e64 s[10:11], s54, v242
	v_cmp_eq_u32_e64 s[12:13], s6, v242
	v_add_f32_e32 v202, v202, v210
	s_or_b64 s[8:9], s[8:9], s[10:11]
	s_or_b64 s[8:9], s[8:9], s[12:13]
	v_cmp_lt_i32_e64 s[14:15], s54, v242
	s_nop 0
	v_cndmask_b32_e64 v0, 0, v159, s[8:9]
	s_nop 0
	v_add_f32_e32 v202, v0, v202
	v_cndmask_b32_e64 v36, v202, v4, s[14:15]
	ds_write_b32 v24, v36 offset:4288
	v_cmp_eq_u32_e64 s[8:9], 0, v243
	v_cmp_eq_u32_e64 s[10:11], s54, v243
	v_cmp_eq_u32_e64 s[12:13], s6, v243
	v_add_f32_e32 v203, v203, v211
	s_or_b64 s[8:9], s[8:9], s[10:11]
	s_or_b64 s[8:9], s[8:9], s[12:13]
	v_cmp_lt_i32_e64 s[14:15], s54, v243
	s_nop 0
	v_cndmask_b32_e64 v0, 0, v159, s[8:9]
	s_nop 0
	v_add_f32_e32 v203, v0, v203
	v_cndmask_b32_e64 v35, v203, v4, s[14:15]
	ds_write_b32 v24, v35 offset:4304
	v_cmp_eq_u32_e64 s[8:9], 0, v244
	v_cmp_eq_u32_e64 s[10:11], s54, v244
	v_cmp_eq_u32_e64 s[12:13], s6, v244
	v_add_f32_e32 v204, v204, v212
	s_or_b64 s[8:9], s[8:9], s[10:11]
	s_or_b64 s[8:9], s[8:9], s[12:13]
	v_cmp_lt_i32_e64 s[14:15], s54, v244
	s_nop 0
	v_cndmask_b32_e64 v0, 0, v159, s[8:9]
	s_nop 0
	v_add_f32_e32 v204, v0, v204
	v_cndmask_b32_e64 v34, v204, v4, s[14:15]
	ds_write_b32 v24, v34 offset:4320
	v_cmp_eq_u32_e64 s[8:9], 0, v245
	v_cmp_eq_u32_e64 s[10:11], s54, v245
	v_cmp_eq_u32_e64 s[12:13], s6, v245
	v_add_f32_e32 v205, v205, v213
	s_or_b64 s[8:9], s[8:9], s[10:11]
	s_or_b64 s[8:9], s[8:9], s[12:13]
	v_cmp_lt_i32_e64 s[14:15], s54, v245
	s_nop 0
	v_cndmask_b32_e64 v0, 0, v159, s[8:9]
	s_nop 0
	v_add_f32_e32 v205, v0, v205
	v_cndmask_b32_e64 v33, v205, v4, s[14:15]
	ds_write_b32 v24, v33 offset:4336
	s_waitcnt lgkmcnt(0)
	s_barrier
; #define LAS __attribute__((address_space(3)))
; DI void attn_phase(const Params& p, const int layer, const int wid_s) {
;     ...
;       int cnt[8];
; #pragma unroll
;       for (int nt = 0; nt < 8; ++nt) cnt[nt] = 0;
; #pragma unroll
;       for (int i = 0; i < 8; ++i) {
;         const f32x4 r4 = *(const LAS f32x4*)(impb + 4 * i);
;         const float rv[4] = {r4[0], r4[1], r4[2], r4[3]};
; #pragma unroll
;         for (int nt = 0; nt < 8; ++nt) {
;           const float a = impv[nt]; const int ja = nt * 4 + fql;
; #pragma unroll
;           for (int c = 0; c < 4; ++c) cnt[nt] += (int)(rv[c] > a) | ((int)(rv[c] == a) & (int)((4 * i + c) < ja));
;         }
;       }
	ds_read_b128 v[198:201], v147 offset:4224
	ds_read_b128 v[202:205], v147 offset:4240
	ds_read_b128 v[206:209], v147 offset:4256
	ds_read_b128 v[210:213], v147 offset:4272
	ds_read_b128 v[214:217], v147 offset:4288
	ds_read_b128 v[218:221], v147 offset:4304
	ds_read_b128 v[222:225], v147 offset:4320
	ds_read_b128 v[226:229], v147 offset:4336
	v_cmp_lt_i32_e64 s[6:7], 0, v123
	v_cmp_lt_i32_e64 s[8:9], 1, v123
	v_cmp_lt_i32_e64 s[10:11], 2, v123
	v_mov_b32_e32 v230, 0
	v_mov_b32_e32 v231, 0
	v_mov_b32_e32 v232, 0
	v_mov_b32_e32 v233, 0
	v_mov_b32_e32 v234, 0
	v_mov_b32_e32 v235, 0
	v_mov_b32_e32 v236, 0
	v_mov_b32_e32 v237, 0
	s_waitcnt lgkmcnt(0)
	v_cmp_gt_f32_e64 s[12:13], v198, v39
	v_cmp_ge_f32_e64 s[20:21], v198, v39
	s_and_b64 s[20:21], s[20:21], s[6:7]
	s_or_b64 s[12:13], s[12:13], s[20:21]
	v_cmp_gt_f32_e64 s[14:15], v199, v39
	v_cmp_ge_f32_e64 s[20:21], v199, v39
	s_and_b64 s[20:21], s[20:21], s[8:9]
	s_or_b64 s[14:15], s[14:15], s[20:21]
	v_cmp_gt_f32_e64 s[16:17], v200, v39
	v_cmp_ge_f32_e64 s[20:21], v200, v39
	s_and_b64 s[20:21], s[20:21], s[10:11]
	s_or_b64 s[16:17], s[16:17], s[20:21]
	v_addc_co_u32_e64 v230, s[18:19], 0, v230, s[12:13]
	v_cmp_gt_f32_e64 s[12:13], v201, v39
	v_addc_co_u32_e64 v230, s[18:19], 0, v230, s[14:15]
	v_cmp_gt_f32_e64 s[14:15], v202, v39
	v_addc_co_u32_e64 v230, s[18:19], 0, v230, s[16:17]
	v_cmp_gt_f32_e64 s[16:17], v203, v39
	v_addc_co_u32_e64 v230, s[18:19], 0, v230, s[12:13]
	v_cmp_gt_f32_e64 s[12:13], v204, v39
	v_addc_co_u32_e64 v230, s[18:19], 0, v230, s[14:15]
	v_cmp_gt_f32_e64 s[14:15], v205, v39
	v_addc_co_u32_e64 v230, s[18:19], 0, v230, s[16:17]
	v_cmp_gt_f32_e64 s[16:17], v206, v39
	v_addc_co_u32_e64 v230, s[18:19], 0, v230, s[12:13]
	v_cmp_gt_f32_e64 s[12:13], v207, v39
	v_addc_co_u32_e64 v230, s[18:19], 0, v230, s[14:15]
	v_cmp_gt_f32_e64 s[14:15], v208, v39
	v_addc_co_u32_e64 v230, s[18:19], 0, v230, s[16:17]
	v_cmp_gt_f32_e64 s[16:17], v209, v39
	v_addc_co_u32_e64 v230, s[18:19], 0, v230, s[12:13]
	v_cmp_gt_f32_e64 s[12:13], v210, v39
	v_addc_co_u32_e64 v230, s[18:19], 0, v230, s[14:15]
	v_cmp_gt_f32_e64 s[14:15], v211, v39
	v_addc_co_u32_e64 v230, s[18:19], 0, v230, s[16:17]
	v_cmp_gt_f32_e64 s[16:17], v212, v39
	v_addc_co_u32_e64 v230, s[18:19], 0, v230, s[12:13]
	v_cmp_gt_f32_e64 s[12:13], v213, v39
	v_addc_co_u32_e64 v230, s[18:19], 0, v230, s[14:15]
	v_cmp_gt_f32_e64 s[14:15], v214, v39
	v_addc_co_u32_e64 v230, s[18:19], 0, v230, s[16:17]
	v_cmp_gt_f32_e64 s[16:17], v215, v39
	v_addc_co_u32_e64 v230, s[18:19], 0, v230, s[12:13]
	v_cmp_gt_f32_e64 s[12:13], v216, v39
	v_addc_co_u32_e64 v230, s[18:19], 0, v230, s[14:15]
	v_cmp_gt_f32_e64 s[14:15], v217, v39
	v_addc_co_u32_e64 v230, s[18:19], 0, v230, s[16:17]
	v_cmp_gt_f32_e64 s[16:17], v218, v39
	v_addc_co_u32_e64 v230, s[18:19], 0, v230, s[12:13]
	v_cmp_gt_f32_e64 s[12:13], v219, v39
	v_addc_co_u32_e64 v230, s[18:19], 0, v230, s[14:15]
	v_cmp_gt_f32_e64 s[14:15], v220, v39
	v_addc_co_u32_e64 v230, s[18:19], 0, v230, s[16:17]
	v_cmp_gt_f32_e64 s[16:17], v221, v39
	v_addc_co_u32_e64 v230, s[18:19], 0, v230, s[12:13]
	v_cmp_gt_f32_e64 s[12:13], v222, v39
	v_addc_co_u32_e64 v230, s[18:19], 0, v230, s[14:15]
	v_cmp_gt_f32_e64 s[14:15], v223, v39
	v_addc_co_u32_e64 v230, s[18:19], 0, v230, s[16:17]
	v_cmp_gt_f32_e64 s[16:17], v224, v39
	v_addc_co_u32_e64 v230, s[18:19], 0, v230, s[12:13]
	v_cmp_gt_f32_e64 s[12:13], v225, v39
	v_addc_co_u32_e64 v230, s[18:19], 0, v230, s[14:15]
	v_cmp_gt_f32_e64 s[14:15], v226, v39
	v_addc_co_u32_e64 v230, s[18:19], 0, v230, s[16:17]
	v_cmp_gt_f32_e64 s[16:17], v227, v39
	v_addc_co_u32_e64 v230, s[18:19], 0, v230, s[12:13]
	v_cmp_gt_f32_e64 s[12:13], v228, v39
	v_addc_co_u32_e64 v230, s[18:19], 0, v230, s[14:15]
	v_cmp_gt_f32_e64 s[14:15], v229, v39
	v_addc_co_u32_e64 v230, s[18:19], 0, v230, s[16:17]
	v_cmp_ge_f32_e64 s[16:17], v198, v40
	v_addc_co_u32_e64 v230, s[18:19], 0, v230, s[12:13]
	v_cmp_ge_f32_e64 s[12:13], v199, v40
	v_addc_co_u32_e64 v230, s[18:19], 0, v230, s[14:15]
	v_cmp_ge_f32_e64 s[14:15], v200, v40
	v_addc_co_u32_e64 v231, s[18:19], 0, v231, s[16:17]
	v_cmp_ge_f32_e64 s[16:17], v201, v40
	v_addc_co_u32_e64 v231, s[18:19], 0, v231, s[12:13]
	v_cmp_gt_f32_e64 s[12:13], v202, v40
	v_cmp_ge_f32_e64 s[20:21], v202, v40
	s_and_b64 s[20:21], s[20:21], s[6:7]
	s_or_b64 s[12:13], s[12:13], s[20:21]
	v_addc_co_u32_e64 v231, s[18:19], 0, v231, s[14:15]
	v_cmp_gt_f32_e64 s[14:15], v203, v40
	v_cmp_ge_f32_e64 s[20:21], v203, v40
	s_and_b64 s[20:21], s[20:21], s[8:9]
	s_or_b64 s[14:15], s[14:15], s[20:21]
	v_addc_co_u32_e64 v231, s[18:19], 0, v231, s[16:17]
	v_cmp_gt_f32_e64 s[16:17], v204, v40
	v_cmp_ge_f32_e64 s[20:21], v204, v40
	s_and_b64 s[20:21], s[20:21], s[10:11]
	s_or_b64 s[16:17], s[16:17], s[20:21]
	v_addc_co_u32_e64 v231, s[18:19], 0, v231, s[12:13]
	v_cmp_gt_f32_e64 s[12:13], v205, v40
	v_addc_co_u32_e64 v231, s[18:19], 0, v231, s[14:15]
	v_cmp_gt_f32_e64 s[14:15], v206, v40
	v_addc_co_u32_e64 v231, s[18:19], 0, v231, s[16:17]
	v_cmp_gt_f32_e64 s[16:17], v207, v40
	v_addc_co_u32_e64 v231, s[18:19], 0, v231, s[12:13]
	v_cmp_gt_f32_e64 s[12:13], v208, v40
	v_addc_co_u32_e64 v231, s[18:19], 0, v231, s[14:15]
	v_cmp_gt_f32_e64 s[14:15], v209, v40
	v_addc_co_u32_e64 v231, s[18:19], 0, v231, s[16:17]
	v_cmp_gt_f32_e64 s[16:17], v210, v40
	v_addc_co_u32_e64 v231, s[18:19], 0, v231, s[12:13]
	v_cmp_gt_f32_e64 s[12:13], v211, v40
	v_addc_co_u32_e64 v231, s[18:19], 0, v231, s[14:15]
	v_cmp_gt_f32_e64 s[14:15], v212, v40
	v_addc_co_u32_e64 v231, s[18:19], 0, v231, s[16:17]
	v_cmp_gt_f32_e64 s[16:17], v213, v40
	v_addc_co_u32_e64 v231, s[18:19], 0, v231, s[12:13]
	v_cmp_gt_f32_e64 s[12:13], v214, v40
; #define LAS __attribute__((address_space(3)))
; DI void attn_phase(const Params& p, const int layer, const int wid_s) {
;     ...
;       for (int i = 0; i < 8; ++i) {
;         const f32x4 r4 = *(const LAS f32x4*)(impb + 4 * i);
;         const float rv[4] = {r4[0], r4[1], r4[2], r4[3]};
; #pragma unroll
;         for (int nt = 0; nt < 8; ++nt) {
;           const float a = impv[nt]; const int ja = nt * 4 + fql;
; #pragma unroll
;           for (int c = 0; c < 4; ++c) cnt[nt] += (int)(rv[c] > a) | ((int)(rv[c] == a) & (int)((4 * i + c) < ja));
;         }
;       }
	v_addc_co_u32_e64 v231, s[18:19], 0, v231, s[14:15]
	v_cmp_gt_f32_e64 s[14:15], v215, v40
	v_addc_co_u32_e64 v231, s[18:19], 0, v231, s[16:17]
	v_cmp_gt_f32_e64 s[16:17], v216, v40
	v_addc_co_u32_e64 v231, s[18:19], 0, v231, s[12:13]
	v_cmp_gt_f32_e64 s[12:13], v217, v40
	v_addc_co_u32_e64 v231, s[18:19], 0, v231, s[14:15]
	v_cmp_gt_f32_e64 s[14:15], v218, v40
	v_addc_co_u32_e64 v231, s[18:19], 0, v231, s[16:17]
	v_cmp_gt_f32_e64 s[16:17], v219, v40
	v_addc_co_u32_e64 v231, s[18:19], 0, v231, s[12:13]
	v_cmp_gt_f32_e64 s[12:13], v220, v40
	v_addc_co_u32_e64 v231, s[18:19], 0, v231, s[14:15]
	v_cmp_gt_f32_e64 s[14:15], v221, v40
	v_addc_co_u32_e64 v231, s[18:19], 0, v231, s[16:17]
	v_cmp_gt_f32_e64 s[16:17], v222, v40
	v_addc_co_u32_e64 v231, s[18:19], 0, v231, s[12:13]
	v_cmp_gt_f32_e64 s[12:13], v223, v40
	v_addc_co_u32_e64 v231, s[18:19], 0, v231, s[14:15]
	v_cmp_gt_f32_e64 s[14:15], v224, v40
	v_addc_co_u32_e64 v231, s[18:19], 0, v231, s[16:17]
	v_cmp_gt_f32_e64 s[16:17], v225, v40
	v_addc_co_u32_e64 v231, s[18:19], 0, v231, s[12:13]
	v_cmp_gt_f32_e64 s[12:13], v226, v40
	v_addc_co_u32_e64 v231, s[18:19], 0, v231, s[14:15]
	v_cmp_gt_f32_e64 s[14:15], v227, v40
	v_addc_co_u32_e64 v231, s[18:19], 0, v231, s[16:17]
	v_cmp_gt_f32_e64 s[16:17], v228, v40
	v_addc_co_u32_e64 v231, s[18:19], 0, v231, s[12:13]
	v_cmp_gt_f32_e64 s[12:13], v229, v40
	v_addc_co_u32_e64 v231, s[18:19], 0, v231, s[14:15]
	v_cmp_ge_f32_e64 s[14:15], v198, v38
	v_addc_co_u32_e64 v231, s[18:19], 0, v231, s[16:17]
	v_cmp_ge_f32_e64 s[16:17], v199, v38
	v_addc_co_u32_e64 v231, s[18:19], 0, v231, s[12:13]
	v_cmp_ge_f32_e64 s[12:13], v200, v38
	v_addc_co_u32_e64 v232, s[18:19], 0, v232, s[14:15]
	v_cmp_ge_f32_e64 s[14:15], v201, v38
	v_addc_co_u32_e64 v232, s[18:19], 0, v232, s[16:17]
	v_cmp_ge_f32_e64 s[16:17], v202, v38
	v_addc_co_u32_e64 v232, s[18:19], 0, v232, s[12:13]
	v_cmp_ge_f32_e64 s[12:13], v203, v38
	v_addc_co_u32_e64 v232, s[18:19], 0, v232, s[14:15]
	v_cmp_ge_f32_e64 s[14:15], v204, v38
	v_addc_co_u32_e64 v232, s[18:19], 0, v232, s[16:17]
	v_cmp_ge_f32_e64 s[16:17], v205, v38
	v_addc_co_u32_e64 v232, s[18:19], 0, v232, s[12:13]
	v_cmp_gt_f32_e64 s[12:13], v206, v38
	v_cmp_ge_f32_e64 s[20:21], v206, v38
	s_and_b64 s[20:21], s[20:21], s[6:7]
	s_or_b64 s[12:13], s[12:13], s[20:21]
	v_addc_co_u32_e64 v232, s[18:19], 0, v232, s[14:15]
	v_cmp_gt_f32_e64 s[14:15], v207, v38
	v_cmp_ge_f32_e64 s[20:21], v207, v38
	s_and_b64 s[20:21], s[20:21], s[8:9]
	s_or_b64 s[14:15], s[14:15], s[20:21]
	v_addc_co_u32_e64 v232, s[18:19], 0, v232, s[16:17]
	v_cmp_gt_f32_e64 s[16:17], v208, v38
	v_cmp_ge_f32_e64 s[20:21], v208, v38
	s_and_b64 s[20:21], s[20:21], s[10:11]
	s_or_b64 s[16:17], s[16:17], s[20:21]
	v_addc_co_u32_e64 v232, s[18:19], 0, v232, s[12:13]
	v_cmp_gt_f32_e64 s[12:13], v209, v38
	v_addc_co_u32_e64 v232, s[18:19], 0, v232, s[14:15]
	v_cmp_gt_f32_e64 s[14:15], v210, v38
	v_addc_co_u32_e64 v232, s[18:19], 0, v232, s[16:17]
	v_cmp_gt_f32_e64 s[16:17], v211, v38
	v_addc_co_u32_e64 v232, s[18:19], 0, v232, s[12:13]
	v_cmp_gt_f32_e64 s[12:13], v212, v38
	v_addc_co_u32_e64 v232, s[18:19], 0, v232, s[14:15]
	v_cmp_gt_f32_e64 s[14:15], v213, v38
	v_addc_co_u32_e64 v232, s[18:19], 0, v232, s[16:17]
	v_cmp_gt_f32_e64 s[16:17], v214, v38
	v_addc_co_u32_e64 v232, s[18:19], 0, v232, s[12:13]
	v_cmp_gt_f32_e64 s[12:13], v215, v38
	v_addc_co_u32_e64 v232, s[18:19], 0, v232, s[14:15]
	v_cmp_gt_f32_e64 s[14:15], v216, v38
	v_addc_co_u32_e64 v232, s[18:19], 0, v232, s[16:17]
	v_cmp_gt_f32_e64 s[16:17], v217, v38
	v_addc_co_u32_e64 v232, s[18:19], 0, v232, s[12:13]
	v_cmp_gt_f32_e64 s[12:13], v218, v38
	v_addc_co_u32_e64 v232, s[18:19], 0, v232, s[14:15]
	v_cmp_gt_f32_e64 s[14:15], v219, v38
	v_addc_co_u32_e64 v232, s[18:19], 0, v232, s[16:17]
	v_cmp_gt_f32_e64 s[16:17], v220, v38
	v_addc_co_u32_e64 v232, s[18:19], 0, v232, s[12:13]
	v_cmp_gt_f32_e64 s[12:13], v221, v38
	v_addc_co_u32_e64 v232, s[18:19], 0, v232, s[14:15]
	v_cmp_gt_f32_e64 s[14:15], v222, v38
	v_addc_co_u32_e64 v232, s[18:19], 0, v232, s[16:17]
	v_cmp_gt_f32_e64 s[16:17], v223, v38
	v_addc_co_u32_e64 v232, s[18:19], 0, v232, s[12:13]
	v_cmp_gt_f32_e64 s[12:13], v224, v38
	v_addc_co_u32_e64 v232, s[18:19], 0, v232, s[14:15]
	v_cmp_gt_f32_e64 s[14:15], v225, v38
	v_addc_co_u32_e64 v232, s[18:19], 0, v232, s[16:17]
	v_cmp_gt_f32_e64 s[16:17], v226, v38
	v_addc_co_u32_e64 v232, s[18:19], 0, v232, s[12:13]
	v_cmp_gt_f32_e64 s[12:13], v227, v38
	v_addc_co_u32_e64 v232, s[18:19], 0, v232, s[14:15]
	v_cmp_gt_f32_e64 s[14:15], v228, v38
	v_addc_co_u32_e64 v232, s[18:19], 0, v232, s[16:17]
	v_cmp_gt_f32_e64 s[16:17], v229, v38
	v_addc_co_u32_e64 v232, s[18:19], 0, v232, s[12:13]
	v_cmp_ge_f32_e64 s[12:13], v198, v37
	v_addc_co_u32_e64 v232, s[18:19], 0, v232, s[14:15]
	v_cmp_ge_f32_e64 s[14:15], v199, v37
	v_addc_co_u32_e64 v232, s[18:19], 0, v232, s[16:17]
	v_cmp_ge_f32_e64 s[16:17], v200, v37
	v_addc_co_u32_e64 v233, s[18:19], 0, v233, s[12:13]
	v_cmp_ge_f32_e64 s[12:13], v201, v37
	v_addc_co_u32_e64 v233, s[18:19], 0, v233, s[14:15]
	v_cmp_ge_f32_e64 s[14:15], v202, v37
	v_addc_co_u32_e64 v233, s[18:19], 0, v233, s[16:17]
	v_cmp_ge_f32_e64 s[16:17], v203, v37
	v_addc_co_u32_e64 v233, s[18:19], 0, v233, s[12:13]
	v_cmp_ge_f32_e64 s[12:13], v204, v37
	v_addc_co_u32_e64 v233, s[18:19], 0, v233, s[14:15]
	v_cmp_ge_f32_e64 s[14:15], v205, v37
	v_addc_co_u32_e64 v233, s[18:19], 0, v233, s[16:17]
	v_cmp_ge_f32_e64 s[16:17], v206, v37
	v_addc_co_u32_e64 v233, s[18:19], 0, v233, s[12:13]
	v_cmp_ge_f32_e64 s[12:13], v207, v37
	v_addc_co_u32_e64 v233, s[18:19], 0, v233, s[14:15]
	v_cmp_ge_f32_e64 s[14:15], v208, v37
; #define LAS __attribute__((address_space(3)))
; DI void attn_phase(const Params& p, const int layer, const int wid_s) {
;     ...
;       for (int i = 0; i < 8; ++i) {
;         const f32x4 r4 = *(const LAS f32x4*)(impb + 4 * i);
;         const float rv[4] = {r4[0], r4[1], r4[2], r4[3]};
; #pragma unroll
;         for (int nt = 0; nt < 8; ++nt) {
;           const float a = impv[nt]; const int ja = nt * 4 + fql;
; #pragma unroll
;           for (int c = 0; c < 4; ++c) cnt[nt] += (int)(rv[c] > a) | ((int)(rv[c] == a) & (int)((4 * i + c) < ja));
;         }
;       }
	v_addc_co_u32_e64 v233, s[18:19], 0, v233, s[16:17]
	v_cmp_ge_f32_e64 s[16:17], v209, v37
	v_addc_co_u32_e64 v233, s[18:19], 0, v233, s[12:13]
	v_cmp_gt_f32_e64 s[12:13], v210, v37
	v_cmp_ge_f32_e64 s[20:21], v210, v37
	s_and_b64 s[20:21], s[20:21], s[6:7]
	s_or_b64 s[12:13], s[12:13], s[20:21]
	v_addc_co_u32_e64 v233, s[18:19], 0, v233, s[14:15]
	v_cmp_gt_f32_e64 s[14:15], v211, v37
	v_cmp_ge_f32_e64 s[20:21], v211, v37
	s_and_b64 s[20:21], s[20:21], s[8:9]
	s_or_b64 s[14:15], s[14:15], s[20:21]
	v_addc_co_u32_e64 v233, s[18:19], 0, v233, s[16:17]
	v_cmp_gt_f32_e64 s[16:17], v212, v37
	v_cmp_ge_f32_e64 s[20:21], v212, v37
	s_and_b64 s[20:21], s[20:21], s[10:11]
	s_or_b64 s[16:17], s[16:17], s[20:21]
	v_addc_co_u32_e64 v233, s[18:19], 0, v233, s[12:13]
	v_cmp_gt_f32_e64 s[12:13], v213, v37
	v_addc_co_u32_e64 v233, s[18:19], 0, v233, s[14:15]
	v_cmp_gt_f32_e64 s[14:15], v214, v37
	v_addc_co_u32_e64 v233, s[18:19], 0, v233, s[16:17]
	v_cmp_gt_f32_e64 s[16:17], v215, v37
	v_addc_co_u32_e64 v233, s[18:19], 0, v233, s[12:13]
	v_cmp_gt_f32_e64 s[12:13], v216, v37
	v_addc_co_u32_e64 v233, s[18:19], 0, v233, s[14:15]
	v_cmp_gt_f32_e64 s[14:15], v217, v37
	v_addc_co_u32_e64 v233, s[18:19], 0, v233, s[16:17]
	v_cmp_gt_f32_e64 s[16:17], v218, v37
	v_addc_co_u32_e64 v233, s[18:19], 0, v233, s[12:13]
	v_cmp_gt_f32_e64 s[12:13], v219, v37
	v_addc_co_u32_e64 v233, s[18:19], 0, v233, s[14:15]
	v_cmp_gt_f32_e64 s[14:15], v220, v37
	v_addc_co_u32_e64 v233, s[18:19], 0, v233, s[16:17]
	v_cmp_gt_f32_e64 s[16:17], v221, v37
	v_addc_co_u32_e64 v233, s[18:19], 0, v233, s[12:13]
	v_cmp_gt_f32_e64 s[12:13], v222, v37
	v_addc_co_u32_e64 v233, s[18:19], 0, v233, s[14:15]
	v_cmp_gt_f32_e64 s[14:15], v223, v37
	v_addc_co_u32_e64 v233, s[18:19], 0, v233, s[16:17]
	v_cmp_gt_f32_e64 s[16:17], v224, v37
	v_addc_co_u32_e64 v233, s[18:19], 0, v233, s[12:13]
	v_cmp_gt_f32_e64 s[12:13], v225, v37
	v_addc_co_u32_e64 v233, s[18:19], 0, v233, s[14:15]
	v_cmp_gt_f32_e64 s[14:15], v226, v37
	v_addc_co_u32_e64 v233, s[18:19], 0, v233, s[16:17]
	v_cmp_gt_f32_e64 s[16:17], v227, v37
	v_addc_co_u32_e64 v233, s[18:19], 0, v233, s[12:13]
	v_cmp_gt_f32_e64 s[12:13], v228, v37
	v_addc_co_u32_e64 v233, s[18:19], 0, v233, s[14:15]
	v_cmp_gt_f32_e64 s[14:15], v229, v37
	v_addc_co_u32_e64 v233, s[18:19], 0, v233, s[16:17]
	v_cmp_ge_f32_e64 s[16:17], v198, v36
	v_addc_co_u32_e64 v233, s[18:19], 0, v233, s[12:13]
	v_cmp_ge_f32_e64 s[12:13], v199, v36
	v_addc_co_u32_e64 v233, s[18:19], 0, v233, s[14:15]
	v_cmp_ge_f32_e64 s[14:15], v200, v36
	v_addc_co_u32_e64 v234, s[18:19], 0, v234, s[16:17]
	v_cmp_ge_f32_e64 s[16:17], v201, v36
	v_addc_co_u32_e64 v234, s[18:19], 0, v234, s[12:13]
	v_cmp_ge_f32_e64 s[12:13], v202, v36
	v_addc_co_u32_e64 v234, s[18:19], 0, v234, s[14:15]
	v_cmp_ge_f32_e64 s[14:15], v203, v36
	v_addc_co_u32_e64 v234, s[18:19], 0, v234, s[16:17]
	v_cmp_ge_f32_e64 s[16:17], v204, v36
	v_addc_co_u32_e64 v234, s[18:19], 0, v234, s[12:13]
	v_cmp_ge_f32_e64 s[12:13], v205, v36
	v_addc_co_u32_e64 v234, s[18:19], 0, v234, s[14:15]
	v_cmp_ge_f32_e64 s[14:15], v206, v36
	v_addc_co_u32_e64 v234, s[18:19], 0, v234, s[16:17]
	v_cmp_ge_f32_e64 s[16:17], v207, v36
	v_addc_co_u32_e64 v234, s[18:19], 0, v234, s[12:13]
	v_cmp_ge_f32_e64 s[12:13], v208, v36
	v_addc_co_u32_e64 v234, s[18:19], 0, v234, s[14:15]
	v_cmp_ge_f32_e64 s[14:15], v209, v36
	v_addc_co_u32_e64 v234, s[18:19], 0, v234, s[16:17]
	v_cmp_ge_f32_e64 s[16:17], v210, v36
	v_addc_co_u32_e64 v234, s[18:19], 0, v234, s[12:13]
	v_cmp_ge_f32_e64 s[12:13], v211, v36
	v_addc_co_u32_e64 v234, s[18:19], 0, v234, s[14:15]
	v_cmp_ge_f32_e64 s[14:15], v212, v36
	v_addc_co_u32_e64 v234, s[18:19], 0, v234, s[16:17]
	v_cmp_ge_f32_e64 s[16:17], v213, v36
	v_addc_co_u32_e64 v234, s[18:19], 0, v234, s[12:13]
	v_cmp_gt_f32_e64 s[12:13], v214, v36
	v_cmp_ge_f32_e64 s[20:21], v214, v36
	s_and_b64 s[20:21], s[20:21], s[6:7]
	s_or_b64 s[12:13], s[12:13], s[20:21]
	v_addc_co_u32_e64 v234, s[18:19], 0, v234, s[14:15]
	v_cmp_gt_f32_e64 s[14:15], v215, v36
	v_cmp_ge_f32_e64 s[20:21], v215, v36
	s_and_b64 s[20:21], s[20:21], s[8:9]
	s_or_b64 s[14:15], s[14:15], s[20:21]
	v_addc_co_u32_e64 v234, s[18:19], 0, v234, s[16:17]
	v_cmp_gt_f32_e64 s[16:17], v216, v36
	v_cmp_ge_f32_e64 s[20:21], v216, v36
	s_and_b64 s[20:21], s[20:21], s[10:11]
	s_or_b64 s[16:17], s[16:17], s[20:21]
	v_addc_co_u32_e64 v234, s[18:19], 0, v234, s[12:13]
	v_cmp_gt_f32_e64 s[12:13], v217, v36
	v_addc_co_u32_e64 v234, s[18:19], 0, v234, s[14:15]
	v_cmp_gt_f32_e64 s[14:15], v218, v36
	v_addc_co_u32_e64 v234, s[18:19], 0, v234, s[16:17]
	v_cmp_gt_f32_e64 s[16:17], v219, v36
	v_addc_co_u32_e64 v234, s[18:19], 0, v234, s[12:13]
	v_cmp_gt_f32_e64 s[12:13], v220, v36
	v_addc_co_u32_e64 v234, s[18:19], 0, v234, s[14:15]
	v_cmp_gt_f32_e64 s[14:15], v221, v36
	v_addc_co_u32_e64 v234, s[18:19], 0, v234, s[16:17]
	v_cmp_gt_f32_e64 s[16:17], v222, v36
	v_addc_co_u32_e64 v234, s[18:19], 0, v234, s[12:13]
	v_cmp_gt_f32_e64 s[12:13], v223, v36
	v_addc_co_u32_e64 v234, s[18:19], 0, v234, s[14:15]
	v_cmp_gt_f32_e64 s[14:15], v224, v36
	v_addc_co_u32_e64 v234, s[18:19], 0, v234, s[16:17]
	v_cmp_gt_f32_e64 s[16:17], v225, v36
	v_addc_co_u32_e64 v234, s[18:19], 0, v234, s[12:13]
	v_cmp_gt_f32_e64 s[12:13], v226, v36
	v_addc_co_u32_e64 v234, s[18:19], 0, v234, s[14:15]
	v_cmp_gt_f32_e64 s[14:15], v227, v36
	v_addc_co_u32_e64 v234, s[18:19], 0, v234, s[16:17]
	v_cmp_gt_f32_e64 s[16:17], v228, v36
	v_addc_co_u32_e64 v234, s[18:19], 0, v234, s[12:13]
	v_cmp_gt_f32_e64 s[12:13], v229, v36
	v_addc_co_u32_e64 v234, s[18:19], 0, v234, s[14:15]
	v_cmp_ge_f32_e64 s[14:15], v198, v35
	v_addc_co_u32_e64 v234, s[18:19], 0, v234, s[16:17]
; #define LAS __attribute__((address_space(3)))
; DI void attn_phase(const Params& p, const int layer, const int wid_s) {
;     ...
;       for (int i = 0; i < 8; ++i) {
;         const f32x4 r4 = *(const LAS f32x4*)(impb + 4 * i);
;         const float rv[4] = {r4[0], r4[1], r4[2], r4[3]};
; #pragma unroll
;         for (int nt = 0; nt < 8; ++nt) {
;           const float a = impv[nt]; const int ja = nt * 4 + fql;
; #pragma unroll
;           for (int c = 0; c < 4; ++c) cnt[nt] += (int)(rv[c] > a) | ((int)(rv[c] == a) & (int)((4 * i + c) < ja));
;         }
;       }
	v_cmp_ge_f32_e64 s[16:17], v199, v35
	v_addc_co_u32_e64 v234, s[18:19], 0, v234, s[12:13]
	v_cmp_ge_f32_e64 s[12:13], v200, v35
	v_addc_co_u32_e64 v235, s[18:19], 0, v235, s[14:15]
	v_cmp_ge_f32_e64 s[14:15], v201, v35
	v_addc_co_u32_e64 v235, s[18:19], 0, v235, s[16:17]
	v_cmp_ge_f32_e64 s[16:17], v202, v35
	v_addc_co_u32_e64 v235, s[18:19], 0, v235, s[12:13]
	v_cmp_ge_f32_e64 s[12:13], v203, v35
	v_addc_co_u32_e64 v235, s[18:19], 0, v235, s[14:15]
	v_cmp_ge_f32_e64 s[14:15], v204, v35
	v_addc_co_u32_e64 v235, s[18:19], 0, v235, s[16:17]
	v_cmp_ge_f32_e64 s[16:17], v205, v35
	v_addc_co_u32_e64 v235, s[18:19], 0, v235, s[12:13]
	v_cmp_ge_f32_e64 s[12:13], v206, v35
	v_addc_co_u32_e64 v235, s[18:19], 0, v235, s[14:15]
	v_cmp_ge_f32_e64 s[14:15], v207, v35
	v_addc_co_u32_e64 v235, s[18:19], 0, v235, s[16:17]
	v_cmp_ge_f32_e64 s[16:17], v208, v35
	v_addc_co_u32_e64 v235, s[18:19], 0, v235, s[12:13]
	v_cmp_ge_f32_e64 s[12:13], v209, v35
	v_addc_co_u32_e64 v235, s[18:19], 0, v235, s[14:15]
	v_cmp_ge_f32_e64 s[14:15], v210, v35
	v_addc_co_u32_e64 v235, s[18:19], 0, v235, s[16:17]
	v_cmp_ge_f32_e64 s[16:17], v211, v35
	v_addc_co_u32_e64 v235, s[18:19], 0, v235, s[12:13]
	v_cmp_ge_f32_e64 s[12:13], v212, v35
	v_addc_co_u32_e64 v235, s[18:19], 0, v235, s[14:15]
	v_cmp_ge_f32_e64 s[14:15], v213, v35
	v_addc_co_u32_e64 v235, s[18:19], 0, v235, s[16:17]
	v_cmp_ge_f32_e64 s[16:17], v214, v35
	v_addc_co_u32_e64 v235, s[18:19], 0, v235, s[12:13]
	v_cmp_ge_f32_e64 s[12:13], v215, v35
	v_addc_co_u32_e64 v235, s[18:19], 0, v235, s[14:15]
	v_cmp_ge_f32_e64 s[14:15], v216, v35
	v_addc_co_u32_e64 v235, s[18:19], 0, v235, s[16:17]
	v_cmp_ge_f32_e64 s[16:17], v217, v35
	v_addc_co_u32_e64 v235, s[18:19], 0, v235, s[12:13]
	v_cmp_gt_f32_e64 s[12:13], v218, v35
	v_cmp_ge_f32_e64 s[20:21], v218, v35
	s_and_b64 s[20:21], s[20:21], s[6:7]
	s_or_b64 s[12:13], s[12:13], s[20:21]
	v_addc_co_u32_e64 v235, s[18:19], 0, v235, s[14:15]
	v_cmp_gt_f32_e64 s[14:15], v219, v35
	v_cmp_ge_f32_e64 s[20:21], v219, v35
	s_and_b64 s[20:21], s[20:21], s[8:9]
	s_or_b64 s[14:15], s[14:15], s[20:21]
	v_addc_co_u32_e64 v235, s[18:19], 0, v235, s[16:17]
	v_cmp_gt_f32_e64 s[16:17], v220, v35
	v_cmp_ge_f32_e64 s[20:21], v220, v35
	s_and_b64 s[20:21], s[20:21], s[10:11]
	s_or_b64 s[16:17], s[16:17], s[20:21]
	v_addc_co_u32_e64 v235, s[18:19], 0, v235, s[12:13]
	v_cmp_gt_f32_e64 s[12:13], v221, v35
	v_addc_co_u32_e64 v235, s[18:19], 0, v235, s[14:15]
	v_cmp_gt_f32_e64 s[14:15], v222, v35
	v_addc_co_u32_e64 v235, s[18:19], 0, v235, s[16:17]
	v_cmp_gt_f32_e64 s[16:17], v223, v35
	v_addc_co_u32_e64 v235, s[18:19], 0, v235, s[12:13]
	v_cmp_gt_f32_e64 s[12:13], v224, v35
	v_addc_co_u32_e64 v235, s[18:19], 0, v235, s[14:15]
	v_cmp_gt_f32_e64 s[14:15], v225, v35
	v_addc_co_u32_e64 v235, s[18:19], 0, v235, s[16:17]
	v_cmp_gt_f32_e64 s[16:17], v226, v35
	v_addc_co_u32_e64 v235, s[18:19], 0, v235, s[12:13]
	v_cmp_gt_f32_e64 s[12:13], v227, v35
	v_addc_co_u32_e64 v235, s[18:19], 0, v235, s[14:15]
	v_cmp_gt_f32_e64 s[14:15], v228, v35
	v_addc_co_u32_e64 v235, s[18:19], 0, v235, s[16:17]
	v_cmp_gt_f32_e64 s[16:17], v229, v35
	v_addc_co_u32_e64 v235, s[18:19], 0, v235, s[12:13]
	v_cmp_ge_f32_e64 s[12:13], v198, v34
	v_addc_co_u32_e64 v235, s[18:19], 0, v235, s[14:15]
	v_cmp_ge_f32_e64 s[14:15], v199, v34
	v_addc_co_u32_e64 v235, s[18:19], 0, v235, s[16:17]
	v_cmp_ge_f32_e64 s[16:17], v200, v34
	v_addc_co_u32_e64 v236, s[18:19], 0, v236, s[12:13]
	v_cmp_ge_f32_e64 s[12:13], v201, v34
	v_addc_co_u32_e64 v236, s[18:19], 0, v236, s[14:15]
	v_cmp_ge_f32_e64 s[14:15], v202, v34
	v_addc_co_u32_e64 v236, s[18:19], 0, v236, s[16:17]
	v_cmp_ge_f32_e64 s[16:17], v203, v34
	v_addc_co_u32_e64 v236, s[18:19], 0, v236, s[12:13]
	v_cmp_ge_f32_e64 s[12:13], v204, v34
	v_addc_co_u32_e64 v236, s[18:19], 0, v236, s[14:15]
	v_cmp_ge_f32_e64 s[14:15], v205, v34
	v_addc_co_u32_e64 v236, s[18:19], 0, v236, s[16:17]
	v_cmp_ge_f32_e64 s[16:17], v206, v34
	v_addc_co_u32_e64 v236, s[18:19], 0, v236, s[12:13]
	v_cmp_ge_f32_e64 s[12:13], v207, v34
	v_addc_co_u32_e64 v236, s[18:19], 0, v236, s[14:15]
	v_cmp_ge_f32_e64 s[14:15], v208, v34
	v_addc_co_u32_e64 v236, s[18:19], 0, v236, s[16:17]
	v_cmp_ge_f32_e64 s[16:17], v209, v34
	v_addc_co_u32_e64 v236, s[18:19], 0, v236, s[12:13]
	v_cmp_ge_f32_e64 s[12:13], v210, v34
	v_addc_co_u32_e64 v236, s[18:19], 0, v236, s[14:15]
	v_cmp_ge_f32_e64 s[14:15], v211, v34
	v_addc_co_u32_e64 v236, s[18:19], 0, v236, s[16:17]
	v_cmp_ge_f32_e64 s[16:17], v212, v34
	v_addc_co_u32_e64 v236, s[18:19], 0, v236, s[12:13]
	v_cmp_ge_f32_e64 s[12:13], v213, v34
	v_addc_co_u32_e64 v236, s[18:19], 0, v236, s[14:15]
	v_cmp_ge_f32_e64 s[14:15], v214, v34
	v_addc_co_u32_e64 v236, s[18:19], 0, v236, s[16:17]
	v_cmp_ge_f32_e64 s[16:17], v215, v34
	v_addc_co_u32_e64 v236, s[18:19], 0, v236, s[12:13]
	v_cmp_ge_f32_e64 s[12:13], v216, v34
	v_addc_co_u32_e64 v236, s[18:19], 0, v236, s[14:15]
	v_cmp_ge_f32_e64 s[14:15], v217, v34
	v_addc_co_u32_e64 v236, s[18:19], 0, v236, s[16:17]
	v_cmp_ge_f32_e64 s[16:17], v218, v34
	v_addc_co_u32_e64 v236, s[18:19], 0, v236, s[12:13]
	v_cmp_ge_f32_e64 s[12:13], v219, v34
	v_addc_co_u32_e64 v236, s[18:19], 0, v236, s[14:15]
	v_cmp_ge_f32_e64 s[14:15], v220, v34
	v_addc_co_u32_e64 v236, s[18:19], 0, v236, s[16:17]
	v_cmp_ge_f32_e64 s[16:17], v221, v34
	v_addc_co_u32_e64 v236, s[18:19], 0, v236, s[12:13]
	v_cmp_gt_f32_e64 s[12:13], v222, v34
	v_cmp_ge_f32_e64 s[20:21], v222, v34
	s_and_b64 s[20:21], s[20:21], s[6:7]
	s_or_b64 s[12:13], s[12:13], s[20:21]
	v_addc_co_u32_e64 v236, s[18:19], 0, v236, s[14:15]
	v_cmp_gt_f32_e64 s[14:15], v223, v34
	v_cmp_ge_f32_e64 s[20:21], v223, v34
; DI int lane_get_i(int v, int srclane) { return __builtin_amdgcn_ds_bpermute(srclane << 2, v); }
; DI void attn_phase(const Params& p, const int layer, const int wid_s) {
;     ...
;           for (int c = 0; c < 4; ++c) cnt[nt] += (int)(rv[c] > a) | ((int)(rv[c] == a) & (int)((4 * i + c) < ja));
;         }
;       }
;       mk = 0;
; #pragma unroll
;       for (int nt = 0; nt < 8; ++nt) { const int ja = nt * 4 + fql; if (cnt[nt] < 8 && ja <= cur) mk |= 1u << ja; }
;       mk |= (unsigned)lane_get_i((int)mk, lane ^ 16);
;       mk |= (unsigned)lane_get_i((int)mk, lane ^ 32);
	s_and_b64 s[20:21], s[20:21], s[8:9]
	s_or_b64 s[14:15], s[14:15], s[20:21]
	v_addc_co_u32_e64 v236, s[18:19], 0, v236, s[16:17]
	v_cmp_gt_f32_e64 s[16:17], v224, v34
	v_cmp_ge_f32_e64 s[20:21], v224, v34
	s_and_b64 s[20:21], s[20:21], s[10:11]
	s_or_b64 s[16:17], s[16:17], s[20:21]
	v_addc_co_u32_e64 v236, s[18:19], 0, v236, s[12:13]
	v_cmp_gt_f32_e64 s[12:13], v225, v34
	v_addc_co_u32_e64 v236, s[18:19], 0, v236, s[14:15]
	v_cmp_gt_f32_e64 s[14:15], v226, v34
	v_addc_co_u32_e64 v236, s[18:19], 0, v236, s[16:17]
	v_cmp_gt_f32_e64 s[16:17], v227, v34
	v_addc_co_u32_e64 v236, s[18:19], 0, v236, s[12:13]
	v_cmp_gt_f32_e64 s[12:13], v228, v34
	v_addc_co_u32_e64 v236, s[18:19], 0, v236, s[14:15]
	v_cmp_gt_f32_e64 s[14:15], v229, v34
	v_addc_co_u32_e64 v236, s[18:19], 0, v236, s[16:17]
	v_cmp_ge_f32_e64 s[16:17], v198, v33
	v_addc_co_u32_e64 v236, s[18:19], 0, v236, s[12:13]
	v_cmp_ge_f32_e64 s[12:13], v199, v33
	v_addc_co_u32_e64 v236, s[18:19], 0, v236, s[14:15]
	v_cmp_ge_f32_e64 s[14:15], v200, v33
	v_addc_co_u32_e64 v237, s[18:19], 0, v237, s[16:17]
	v_cmp_ge_f32_e64 s[16:17], v201, v33
	v_addc_co_u32_e64 v237, s[18:19], 0, v237, s[12:13]
	v_cmp_ge_f32_e64 s[12:13], v202, v33
	v_addc_co_u32_e64 v237, s[18:19], 0, v237, s[14:15]
	v_cmp_ge_f32_e64 s[14:15], v203, v33
	v_addc_co_u32_e64 v237, s[18:19], 0, v237, s[16:17]
	v_cmp_ge_f32_e64 s[16:17], v204, v33
	v_addc_co_u32_e64 v237, s[18:19], 0, v237, s[12:13]
	v_cmp_ge_f32_e64 s[12:13], v205, v33
	v_addc_co_u32_e64 v237, s[18:19], 0, v237, s[14:15]
	v_cmp_ge_f32_e64 s[14:15], v206, v33
	v_addc_co_u32_e64 v237, s[18:19], 0, v237, s[16:17]
	v_cmp_ge_f32_e64 s[16:17], v207, v33
	v_addc_co_u32_e64 v237, s[18:19], 0, v237, s[12:13]
	v_cmp_ge_f32_e64 s[12:13], v208, v33
	v_addc_co_u32_e64 v237, s[18:19], 0, v237, s[14:15]
	v_cmp_ge_f32_e64 s[14:15], v209, v33
	v_addc_co_u32_e64 v237, s[18:19], 0, v237, s[16:17]
	v_cmp_ge_f32_e64 s[16:17], v210, v33
	v_addc_co_u32_e64 v237, s[18:19], 0, v237, s[12:13]
	v_cmp_ge_f32_e64 s[12:13], v211, v33
	v_addc_co_u32_e64 v237, s[18:19], 0, v237, s[14:15]
	v_cmp_ge_f32_e64 s[14:15], v212, v33
	v_addc_co_u32_e64 v237, s[18:19], 0, v237, s[16:17]
	v_cmp_ge_f32_e64 s[16:17], v213, v33
	v_addc_co_u32_e64 v237, s[18:19], 0, v237, s[12:13]
	v_cmp_ge_f32_e64 s[12:13], v214, v33
	v_addc_co_u32_e64 v237, s[18:19], 0, v237, s[14:15]
	v_cmp_ge_f32_e64 s[14:15], v215, v33
	v_addc_co_u32_e64 v237, s[18:19], 0, v237, s[16:17]
	v_cmp_ge_f32_e64 s[16:17], v216, v33
	v_addc_co_u32_e64 v237, s[18:19], 0, v237, s[12:13]
	v_cmp_ge_f32_e64 s[12:13], v217, v33
	v_addc_co_u32_e64 v237, s[18:19], 0, v237, s[14:15]
	v_cmp_ge_f32_e64 s[14:15], v218, v33
	v_addc_co_u32_e64 v237, s[18:19], 0, v237, s[16:17]
	v_cmp_ge_f32_e64 s[16:17], v219, v33
	v_addc_co_u32_e64 v237, s[18:19], 0, v237, s[12:13]
	v_cmp_ge_f32_e64 s[12:13], v220, v33
	v_addc_co_u32_e64 v237, s[18:19], 0, v237, s[14:15]
	v_cmp_ge_f32_e64 s[14:15], v221, v33
	v_addc_co_u32_e64 v237, s[18:19], 0, v237, s[16:17]
	v_cmp_ge_f32_e64 s[16:17], v222, v33
	v_addc_co_u32_e64 v237, s[18:19], 0, v237, s[12:13]
	v_cmp_ge_f32_e64 s[12:13], v223, v33
	v_addc_co_u32_e64 v237, s[18:19], 0, v237, s[14:15]
	v_cmp_ge_f32_e64 s[14:15], v224, v33
	v_addc_co_u32_e64 v237, s[18:19], 0, v237, s[16:17]
	v_cmp_ge_f32_e64 s[16:17], v225, v33
	v_addc_co_u32_e64 v237, s[18:19], 0, v237, s[12:13]
	v_cmp_gt_f32_e64 s[12:13], v226, v33
	v_cmp_ge_f32_e64 s[20:21], v226, v33
	s_and_b64 s[20:21], s[20:21], s[6:7]
	s_or_b64 s[12:13], s[12:13], s[20:21]
	v_addc_co_u32_e64 v237, s[18:19], 0, v237, s[14:15]
	v_cmp_gt_f32_e64 s[14:15], v227, v33
	v_cmp_ge_f32_e64 s[20:21], v227, v33
	s_and_b64 s[20:21], s[20:21], s[8:9]
	s_or_b64 s[14:15], s[14:15], s[20:21]
	v_addc_co_u32_e64 v237, s[18:19], 0, v237, s[16:17]
	v_cmp_gt_f32_e64 s[16:17], v228, v33
	v_cmp_ge_f32_e64 s[20:21], v228, v33
	s_and_b64 s[20:21], s[20:21], s[10:11]
	s_or_b64 s[16:17], s[16:17], s[20:21]
	v_addc_co_u32_e64 v237, s[18:19], 0, v237, s[12:13]
	v_cmp_gt_f32_e64 s[12:13], v229, v33
	v_addc_co_u32_e64 v237, s[18:19], 0, v237, s[14:15]
	s_nop 1
	v_addc_co_u32_e64 v237, s[18:19], 0, v237, s[16:17]
	v_addc_co_u32_e64 v237, s[18:19], 0, v237, s[12:13]
	v_cmp_gt_u32_e64 s[12:13], 8, v230
	v_cmp_ge_i32_e64 s[14:15], s54, v238
	v_lshlrev_b32_e64 v238, v238, 1
	s_and_b64 s[12:13], s[12:13], s[14:15]
	s_nop 1
	v_cndmask_b32_e64 v238, 0, v238, s[12:13]
	v_cmp_gt_u32_e64 s[16:17], 8, v231
	v_cmp_ge_i32_e64 s[20:21], s54, v239
	v_lshlrev_b32_e64 v239, v239, 1
	s_and_b64 s[16:17], s[16:17], s[20:21]
	s_nop 1
	v_cndmask_b32_e64 v239, 0, v239, s[16:17]
	v_cmp_gt_u32_e64 s[12:13], 8, v232
	v_cmp_ge_i32_e64 s[14:15], s54, v240
	v_lshlrev_b32_e64 v240, v240, 1
	s_and_b64 s[12:13], s[12:13], s[14:15]
	s_nop 1
	v_cndmask_b32_e64 v240, 0, v240, s[12:13]
	v_cmp_gt_u32_e64 s[16:17], 8, v233
	v_cmp_ge_i32_e64 s[20:21], s54, v241
	v_lshlrev_b32_e64 v241, v241, 1
	s_and_b64 s[16:17], s[16:17], s[20:21]
	s_nop 1
	v_cndmask_b32_e64 v241, 0, v241, s[16:17]
	v_cmp_gt_u32_e64 s[12:13], 8, v234
	v_cmp_ge_i32_e64 s[14:15], s54, v242
	v_lshlrev_b32_e64 v242, v242, 1
	s_and_b64 s[12:13], s[12:13], s[14:15]
	s_nop 1
	v_cndmask_b32_e64 v242, 0, v242, s[12:13]
	v_cmp_gt_u32_e64 s[16:17], 8, v235
	v_cmp_ge_i32_e64 s[20:21], s54, v243
	v_lshlrev_b32_e64 v243, v243, 1
	s_and_b64 s[16:17], s[16:17], s[20:21]
	s_nop 1
	v_cndmask_b32_e64 v243, 0, v243, s[16:17]
	v_cmp_gt_u32_e64 s[12:13], 8, v236
	v_cmp_ge_i32_e64 s[14:15], s54, v244
	v_lshlrev_b32_e64 v244, v244, 1
	s_and_b64 s[12:13], s[12:13], s[14:15]
	s_nop 1
	v_cndmask_b32_e64 v244, 0, v244, s[12:13]
	v_cmp_gt_u32_e64 s[16:17], 8, v237
	v_cmp_ge_i32_e64 s[20:21], s54, v245
	v_lshlrev_b32_e64 v245, v245, 1
	s_and_b64 s[16:17], s[16:17], s[20:21]
	s_nop 1
	v_cndmask_b32_e64 v245, 0, v245, s[16:17]
	v_or3_b32 v0, v238, v239, v240
	v_or3_b32 v2, v241, v242, v243
	v_or3_b32 v0, v0, v244, v245
	v_or_b32_e32 v0, v0, v2
	ds_bpermute_b32 v2, v179, v0
	s_waitcnt lgkmcnt(0)
	v_or_b32_e32 v0, v0, v2
	ds_bpermute_b32 v2, v180, v0
	s_waitcnt lgkmcnt(0)
	v_or_b32_e32 v5, v0, v2
